# prologue XN row loop: norm weights loaded once, next row prefetched, no waits on stores
# speedup vs baseline: 1.0015x; 1.0015x over previous
.LBB0_119:
	s_or_b64 exec, exec, s[6:7]
	s_cmpk_gt_i32 s8, 0x40ff
	s_cbranch_scc1 .LBB0_122
	v_mbcnt_lo_u32_b32 v0, -1, 0
	v_mbcnt_hi_u32_b32 v0, -1, v0
	v_and_b32_e32 v1, 64, v0
	v_add_u32_e32 v1, 64, v1
	v_xor_b32_e32 v2, 1, v0
	v_cmp_lt_i32_e32 vcc, v2, v1
	s_load_dwordx2 s[4:5], s[10:11], 0x48
	v_ashrrev_i32_e32 v65, 31, v64
	v_cndmask_b32_e32 v2, v0, v2, vcc
	v_lshlrev_b32_e32 v8, 2, v2
	v_xor_b32_e32 v2, 2, v0
	v_cmp_lt_i32_e32 vcc, v2, v1
	s_ashr_i32 s9, s8, 31
	s_waitcnt lgkmcnt(0)
	v_lshl_add_u64 v[4:5], v[64:65], 4, s[4:5]
	v_cndmask_b32_e32 v2, v0, v2, vcc
	v_lshlrev_b32_e32 v9, 2, v2
	v_xor_b32_e32 v2, 4, v0
	v_cmp_lt_i32_e32 vcc, v2, v1
	s_lshl_b64 s[4:5], s[8:9], 11
	s_add_u32 s4, s12, s4
	v_cndmask_b32_e32 v2, v0, v2, vcc
	s_waitcnt vmcnt(1)
	v_lshlrev_b32_e32 v10, 2, v2
	v_xor_b32_e32 v2, 8, v0
	v_cmp_lt_i32_e32 vcc, v2, v1
	s_addc_u32 s5, s13, s5
	s_ashr_i32 s95, s94, 31
	v_cndmask_b32_e32 v2, v0, v2, vcc
	v_lshlrev_b32_e32 v11, 2, v2
	v_xor_b32_e32 v2, 16, v0
	v_cmp_lt_i32_e32 vcc, v2, v1
	s_lshl_b64 s[6:7], s[94:95], 11
	v_mov_b32_e32 v14, 0x358637bd
	v_cndmask_b32_e32 v2, v0, v2, vcc
	v_lshlrev_b32_e32 v12, 2, v2
	v_xor_b32_e32 v2, 32, v0
	v_cmp_lt_i32_e32 vcc, v2, v1
	s_mov_b32 s12, 0xf800000
	v_mov_b32_e32 v15, 0x260
	v_cndmask_b32_e32 v0, v0, v2, vcc
	v_lshlrev_b32_e32 v13, 2, v0
	v_lshl_add_u64 v[0:1], v[64:65], 3, s[4:5]
	s_mov_b64 s[4:5], 0xbe20200
	v_lshl_add_u64 v[6:7], v[0:1], 0, s[4:5]
	s_movk_i32 s13, 0x7fff
	s_mov_b32 s14, 0xffff0000
	s_load_dwordx2 s[24:25], s[10:11], 0x0
	s_load_dwordx2 s[26:27], s[10:11], 0x8
	s_waitcnt lgkmcnt(0)
	s_add_i32 s5, s8, 0xffffc000
	s_cmpk_lt_i32 s8, 0x4000
	s_cselect_b32 s16, s24, s26
	s_cselect_b32 s17, s25, s27
	s_cselect_b32 s4, s8, s5
	s_mov_b32 s5, 0
	s_lshl_b64 s[4:5], s[4:5], 12
	s_add_u32 s4, s16, s4
	s_addc_u32 s5, s17, s5
	v_lshl_add_u64 v[32:33], v[64:65], 4, s[4:5]
	global_load_dwordx4 v[16:19], v[32:33], off
	global_load_dwordx4 v[20:23], v[32:33], off offset:1024
	global_load_dwordx4 v[24:27], v[32:33], off offset:2048
	global_load_dwordx4 v[0:3], v[32:33], off offset:3072
	global_load_dwordx4 v[176:179], v[4:5], off
	global_load_dwordx4 v[180:183], v[4:5], off offset:1024
	global_load_dwordx4 v[184:187], v[4:5], off offset:2048
	global_load_dwordx4 v[188:191], v[4:5], off offset:3072
.Lxn_top:
	s_add_i32 s15, s8, s94
	s_cmpk_lt_i32 s15, 0x4100
	s_cselect_b32 s4, s15, s8
	s_add_i32 s5, s4, 0xffffc000
	s_cmpk_lt_i32 s4, 0x4000
	s_cselect_b32 s16, s24, s26
	s_cselect_b32 s17, s25, s27
	s_cselect_b32 s4, s4, s5
	s_mov_b32 s5, 0
	s_lshl_b64 s[4:5], s[4:5], 12
	s_add_u32 s4, s16, s4
	s_addc_u32 s5, s17, s5
	v_lshl_add_u64 v[32:33], v[64:65], 4, s[4:5]
	global_load_dwordx4 v[192:195], v[32:33], off
	global_load_dwordx4 v[196:199], v[32:33], off offset:1024
	global_load_dwordx4 v[200:203], v[32:33], off offset:2048
	global_load_dwordx4 v[204:207], v[32:33], off offset:3072
	s_waitcnt vmcnt(8)
	v_mul_f32_e32 v32, v17, v17
	v_mul_f32_e32 v33, v19, v19
	v_mul_f32_e32 v34, v21, v21
	v_mul_f32_e32 v35, v23, v23
	v_mul_f32_e32 v36, v25, v25
	v_mul_f32_e32 v37, v27, v27
	v_fmac_f32_e32 v32, v16, v16
	v_fmac_f32_e32 v33, v18, v18
	v_fmac_f32_e32 v34, v20, v20
	v_fmac_f32_e32 v35, v22, v22
	v_mul_f32_e32 v38, v1, v1
	v_mul_f32_e32 v39, v3, v3
	v_fmac_f32_e32 v36, v24, v24
	v_fmac_f32_e32 v37, v26, v26
	v_add_f32_e32 v32, v32, v33
	v_add_f32_e32 v33, v34, v35
	v_fmac_f32_e32 v38, v0, v0
	v_fmac_f32_e32 v39, v2, v2
	v_add_f32_e32 v34, v36, v37
	v_add_f32_e32 v32, v32, v33
	v_add_f32_e32 v35, v38, v39
	v_add_f32_e32 v32, v32, v34
	v_add_f32_e32 v32, v32, v35
	ds_bpermute_b32 v33, v8, v32
	s_waitcnt lgkmcnt(0)
	v_add_f32_e32 v32, v32, v33
	ds_bpermute_b32 v33, v9, v32
	s_waitcnt lgkmcnt(0)
	v_add_f32_e32 v32, v32, v33
	ds_bpermute_b32 v33, v10, v32
	s_waitcnt lgkmcnt(0)
	v_add_f32_e32 v32, v32, v33
	ds_bpermute_b32 v33, v11, v32
	s_waitcnt lgkmcnt(0)
	v_add_f32_e32 v32, v32, v33
	ds_bpermute_b32 v33, v12, v32
	s_waitcnt lgkmcnt(0)
	v_add_f32_e32 v32, v32, v33
	ds_bpermute_b32 v33, v13, v32
	s_waitcnt lgkmcnt(0)
	v_add_f32_e32 v32, v32, v33
	v_fmamk_f32 v32, v32, 0x3a800000, v14
	v_mul_f32_e32 v33, 0x4f800000, v32
	v_cmp_gt_f32_e32 vcc, s12, v32
	s_nop 1
	v_cndmask_b32_e32 v32, v32, v33, vcc
	v_sqrt_f32_e32 v33, v32
	s_nop 0
	v_add_u32_e32 v34, -1, v33
	v_add_u32_e32 v35, 1, v33
	v_fma_f32 v36, -v34, v33, v32
	v_fma_f32 v37, -v35, v33, v32
	v_cmp_ge_f32_e64 s[4:5], 0, v36
	s_nop 1
	v_cndmask_b32_e64 v33, v33, v34, s[4:5]
	v_cmp_lt_f32_e64 s[4:5], 0, v37
	s_nop 1
	v_cndmask_b32_e64 v33, v33, v35, s[4:5]
	v_mul_f32_e32 v34, 0x37800000, v33
	v_cndmask_b32_e32 v33, v33, v34, vcc
	v_cmp_class_f32_e32 vcc, v32, v15
	s_nop 1
	v_cndmask_b32_e32 v32, v33, v32, vcc
	v_div_scale_f32 v33, s[4:5], v32, v32, 1.0
	v_rcp_f32_e32 v35, v33
	v_div_scale_f32 v34, vcc, 1.0, v32, 1.0
	v_fma_f32 v36, -v33, v35, 1.0
	v_fmac_f32_e32 v35, v36, v35
	v_mul_f32_e32 v36, v34, v35
	v_fma_f32 v37, -v33, v36, v34
	v_fmac_f32_e32 v36, v37, v35
	v_fma_f32 v33, -v33, v36, v34
	v_div_fmas_f32 v33, v33, v35, v36
	v_div_fixup_f32 v32, v33, v32, 1.0
	v_mul_f32_e32 v16, v16, v32
	v_mul_f32_e32 v17, v17, v32
	v_mul_f32_e32 v18, v18, v32
	v_mul_f32_e32 v19, v19, v32
	v_mul_f32_e32 v20, v20, v32
	v_mul_f32_e32 v21, v21, v32
	v_mul_f32_e32 v22, v22, v32
	v_mul_f32_e32 v23, v23, v32
	v_mul_f32_e32 v24, v24, v32
	v_mul_f32_e32 v25, v25, v32
	v_mul_f32_e32 v26, v26, v32
	v_mul_f32_e32 v27, v27, v32
	v_mul_f32_e32 v0, v0, v32
	v_mul_f32_e32 v1, v1, v32
	v_mul_f32_e32 v2, v2, v32
	v_mul_f32_e32 v3, v3, v32
	s_waitcnt vmcnt(4)
	v_mul_f32_e32 v16, v176, v16
	v_mul_f32_e32 v17, v177, v17
	v_mul_f32_e32 v18, v178, v18
	v_mul_f32_e32 v19, v179, v19
	v_bfe_u32 v28, v16, 16, 1
	v_bfe_u32 v29, v17, 16, 1
	v_bfe_u32 v30, v18, 16, 1
	v_bfe_u32 v31, v19, 16, 1
	v_add3_u32 v16, v16, v28, s13
	v_add3_u32 v17, v17, v29, s13
	v_add3_u32 v18, v18, v30, s13
	v_add3_u32 v19, v19, v31, s13
	v_lshrrev_b32_e32 v16, 16, v16
	v_lshrrev_b32_e32 v18, 16, v18
	v_and_or_b32 v16, v17, s14, v16
	v_and_or_b32 v17, v19, s14, v18
	global_store_dwordx2 v[6:7], v[16:17], off
	v_mul_f32_e32 v20, v180, v20
	v_mul_f32_e32 v21, v181, v21
	v_mul_f32_e32 v22, v182, v22
	v_mul_f32_e32 v23, v183, v23
	v_bfe_u32 v28, v20, 16, 1
	v_bfe_u32 v29, v21, 16, 1
	v_bfe_u32 v30, v22, 16, 1
	v_bfe_u32 v31, v23, 16, 1
	v_add3_u32 v20, v20, v28, s13
	v_add3_u32 v21, v21, v29, s13
	v_add3_u32 v22, v22, v30, s13
	v_add3_u32 v23, v23, v31, s13
	v_lshrrev_b32_e32 v20, 16, v20
	v_lshrrev_b32_e32 v22, 16, v22
	v_and_or_b32 v20, v21, s14, v20
	v_and_or_b32 v21, v23, s14, v22
	global_store_dwordx2 v[6:7], v[20:21], off offset:512
	v_mul_f32_e32 v24, v184, v24
	v_mul_f32_e32 v25, v185, v25
	v_mul_f32_e32 v26, v186, v26
	v_mul_f32_e32 v27, v187, v27
	v_bfe_u32 v28, v24, 16, 1
	v_bfe_u32 v29, v25, 16, 1
	v_bfe_u32 v30, v26, 16, 1
	v_bfe_u32 v31, v27, 16, 1
	v_add3_u32 v24, v24, v28, s13
	v_add3_u32 v25, v25, v29, s13
	v_add3_u32 v26, v26, v30, s13
	v_add3_u32 v27, v27, v31, s13
	v_lshrrev_b32_e32 v24, 16, v24
	v_lshrrev_b32_e32 v26, 16, v26
	v_and_or_b32 v24, v25, s14, v24
	v_and_or_b32 v25, v27, s14, v26
	global_store_dwordx2 v[6:7], v[24:25], off offset:1024
	v_mul_f32_e32 v0, v188, v0
	v_mul_f32_e32 v1, v189, v1
	v_mul_f32_e32 v2, v190, v2
	v_mul_f32_e32 v3, v191, v3
	v_bfe_u32 v28, v0, 16, 1
	v_bfe_u32 v29, v1, 16, 1
	v_bfe_u32 v30, v2, 16, 1
	v_bfe_u32 v31, v3, 16, 1
	v_add3_u32 v0, v0, v28, s13
	v_add3_u32 v1, v1, v29, s13
	v_add3_u32 v2, v2, v30, s13
	v_add3_u32 v3, v3, v31, s13
	v_lshrrev_b32_e32 v0, 16, v0
	v_lshrrev_b32_e32 v2, 16, v2
	v_and_or_b32 v0, v1, s14, v0
	v_and_or_b32 v1, v3, s14, v2
	global_store_dwordx2 v[6:7], v[0:1], off offset:1536
	v_lshl_add_u64 v[6:7], v[6:7], 0, s[6:7]
	s_mov_b32 s8, s15
	s_cmpk_lt_i32 s8, 0x4100
	s_cbranch_scc0 .Lxn_exit
	s_add_i32 s15, s8, s94
	s_cmpk_lt_i32 s15, 0x4100
	s_cselect_b32 s4, s15, s8
	s_add_i32 s5, s4, 0xffffc000
	s_cmpk_lt_i32 s4, 0x4000
	s_cselect_b32 s16, s24, s26
	s_cselect_b32 s17, s25, s27
	s_cselect_b32 s4, s4, s5
	s_mov_b32 s5, 0
	s_lshl_b64 s[4:5], s[4:5], 12
	s_add_u32 s4, s16, s4
	s_addc_u32 s5, s17, s5
	v_lshl_add_u64 v[32:33], v[64:65], 4, s[4:5]
	global_load_dwordx4 v[16:19], v[32:33], off
	global_load_dwordx4 v[20:23], v[32:33], off offset:1024
	global_load_dwordx4 v[24:27], v[32:33], off offset:2048
	global_load_dwordx4 v[0:3], v[32:33], off offset:3072
	s_waitcnt vmcnt(8)
	v_mul_f32_e32 v32, v193, v193
	v_mul_f32_e32 v33, v195, v195
	v_mul_f32_e32 v34, v197, v197
	v_mul_f32_e32 v35, v199, v199
	v_mul_f32_e32 v36, v201, v201
	v_mul_f32_e32 v37, v203, v203
	v_fmac_f32_e32 v32, v192, v192
	v_fmac_f32_e32 v33, v194, v194
	v_fmac_f32_e32 v34, v196, v196
	v_fmac_f32_e32 v35, v198, v198
	v_mul_f32_e32 v38, v205, v205
	v_mul_f32_e32 v39, v207, v207
	v_fmac_f32_e32 v36, v200, v200
	v_fmac_f32_e32 v37, v202, v202
	v_add_f32_e32 v32, v32, v33
	v_add_f32_e32 v33, v34, v35
	v_fmac_f32_e32 v38, v204, v204
	v_fmac_f32_e32 v39, v206, v206
	v_add_f32_e32 v34, v36, v37
	v_add_f32_e32 v32, v32, v33
	v_add_f32_e32 v35, v38, v39
	v_add_f32_e32 v32, v32, v34
	v_add_f32_e32 v32, v32, v35
	ds_bpermute_b32 v33, v8, v32
	s_waitcnt lgkmcnt(0)
	v_add_f32_e32 v32, v32, v33
	ds_bpermute_b32 v33, v9, v32
	s_waitcnt lgkmcnt(0)
	v_add_f32_e32 v32, v32, v33
	ds_bpermute_b32 v33, v10, v32
	s_waitcnt lgkmcnt(0)
	v_add_f32_e32 v32, v32, v33
	ds_bpermute_b32 v33, v11, v32
	s_waitcnt lgkmcnt(0)
	v_add_f32_e32 v32, v32, v33
	ds_bpermute_b32 v33, v12, v32
	s_waitcnt lgkmcnt(0)
	v_add_f32_e32 v32, v32, v33
	ds_bpermute_b32 v33, v13, v32
	s_waitcnt lgkmcnt(0)
	v_add_f32_e32 v32, v32, v33
	v_fmamk_f32 v32, v32, 0x3a800000, v14
	v_mul_f32_e32 v33, 0x4f800000, v32
	v_cmp_gt_f32_e32 vcc, s12, v32
	s_nop 1
	v_cndmask_b32_e32 v32, v32, v33, vcc
	v_sqrt_f32_e32 v33, v32
	s_nop 0
	v_add_u32_e32 v34, -1, v33
	v_add_u32_e32 v35, 1, v33
	v_fma_f32 v36, -v34, v33, v32
	v_fma_f32 v37, -v35, v33, v32
	v_cmp_ge_f32_e64 s[4:5], 0, v36
	s_nop 1
	v_cndmask_b32_e64 v33, v33, v34, s[4:5]
	v_cmp_lt_f32_e64 s[4:5], 0, v37
	s_nop 1
	v_cndmask_b32_e64 v33, v33, v35, s[4:5]
	v_mul_f32_e32 v34, 0x37800000, v33
	v_cndmask_b32_e32 v33, v33, v34, vcc
	v_cmp_class_f32_e32 vcc, v32, v15
	s_nop 1
	v_cndmask_b32_e32 v32, v33, v32, vcc
	v_div_scale_f32 v33, s[4:5], v32, v32, 1.0
	v_rcp_f32_e32 v35, v33
	v_div_scale_f32 v34, vcc, 1.0, v32, 1.0
	v_fma_f32 v36, -v33, v35, 1.0
	v_fmac_f32_e32 v35, v36, v35
	v_mul_f32_e32 v36, v34, v35
	v_fma_f32 v37, -v33, v36, v34
	v_fmac_f32_e32 v36, v37, v35
	v_fma_f32 v33, -v33, v36, v34
	v_div_fmas_f32 v33, v33, v35, v36
	v_div_fixup_f32 v32, v33, v32, 1.0
	v_mul_f32_e32 v192, v192, v32
	v_mul_f32_e32 v193, v193, v32
	v_mul_f32_e32 v194, v194, v32
	v_mul_f32_e32 v195, v195, v32
	v_mul_f32_e32 v196, v196, v32
	v_mul_f32_e32 v197, v197, v32
	v_mul_f32_e32 v198, v198, v32
	v_mul_f32_e32 v199, v199, v32
	v_mul_f32_e32 v200, v200, v32
	v_mul_f32_e32 v201, v201, v32
	v_mul_f32_e32 v202, v202, v32
	v_mul_f32_e32 v203, v203, v32
	v_mul_f32_e32 v204, v204, v32
	v_mul_f32_e32 v205, v205, v32
	v_mul_f32_e32 v206, v206, v32
	v_mul_f32_e32 v207, v207, v32
	s_waitcnt vmcnt(4)
	v_mul_f32_e32 v192, v176, v192
	v_mul_f32_e32 v193, v177, v193
	v_mul_f32_e32 v194, v178, v194
	v_mul_f32_e32 v195, v179, v195
	v_bfe_u32 v28, v192, 16, 1
	v_bfe_u32 v29, v193, 16, 1
	v_bfe_u32 v30, v194, 16, 1
	v_bfe_u32 v31, v195, 16, 1
	v_add3_u32 v192, v192, v28, s13
	v_add3_u32 v193, v193, v29, s13
	v_add3_u32 v194, v194, v30, s13
	v_add3_u32 v195, v195, v31, s13
	v_lshrrev_b32_e32 v192, 16, v192
	v_lshrrev_b32_e32 v194, 16, v194
	v_and_or_b32 v192, v193, s14, v192
	v_and_or_b32 v193, v195, s14, v194
	global_store_dwordx2 v[6:7], v[192:193], off
	v_mul_f32_e32 v196, v180, v196
	v_mul_f32_e32 v197, v181, v197
	v_mul_f32_e32 v198, v182, v198
	v_mul_f32_e32 v199, v183, v199
	v_bfe_u32 v28, v196, 16, 1
	v_bfe_u32 v29, v197, 16, 1
	v_bfe_u32 v30, v198, 16, 1
	v_bfe_u32 v31, v199, 16, 1
	v_add3_u32 v196, v196, v28, s13
	v_add3_u32 v197, v197, v29, s13
	v_add3_u32 v198, v198, v30, s13
	v_add3_u32 v199, v199, v31, s13
	v_lshrrev_b32_e32 v196, 16, v196
	v_lshrrev_b32_e32 v198, 16, v198
	v_and_or_b32 v196, v197, s14, v196
	v_and_or_b32 v197, v199, s14, v198
	global_store_dwordx2 v[6:7], v[196:197], off offset:512
	v_mul_f32_e32 v200, v184, v200
	v_mul_f32_e32 v201, v185, v201
	v_mul_f32_e32 v202, v186, v202
	v_mul_f32_e32 v203, v187, v203
	v_bfe_u32 v28, v200, 16, 1
	v_bfe_u32 v29, v201, 16, 1
	v_bfe_u32 v30, v202, 16, 1
	v_bfe_u32 v31, v203, 16, 1
	v_add3_u32 v200, v200, v28, s13
	v_add3_u32 v201, v201, v29, s13
	v_add3_u32 v202, v202, v30, s13
	v_add3_u32 v203, v203, v31, s13
	v_lshrrev_b32_e32 v200, 16, v200
	v_lshrrev_b32_e32 v202, 16, v202
	v_and_or_b32 v200, v201, s14, v200
	v_and_or_b32 v201, v203, s14, v202
	global_store_dwordx2 v[6:7], v[200:201], off offset:1024
	v_mul_f32_e32 v204, v188, v204
	v_mul_f32_e32 v205, v189, v205
	v_mul_f32_e32 v206, v190, v206
	v_mul_f32_e32 v207, v191, v207
	v_bfe_u32 v28, v204, 16, 1
	v_bfe_u32 v29, v205, 16, 1
	v_bfe_u32 v30, v206, 16, 1
	v_bfe_u32 v31, v207, 16, 1
	v_add3_u32 v204, v204, v28, s13
	v_add3_u32 v205, v205, v29, s13
	v_add3_u32 v206, v206, v30, s13
	v_add3_u32 v207, v207, v31, s13
	v_lshrrev_b32_e32 v204, 16, v204
	v_lshrrev_b32_e32 v206, 16, v206
	v_and_or_b32 v204, v205, s14, v204
	v_and_or_b32 v205, v207, s14, v206
	global_store_dwordx2 v[6:7], v[204:205], off offset:1536
	v_lshl_add_u64 v[6:7], v[6:7], 0, s[6:7]
	s_mov_b32 s8, s15
	s_cmpk_lt_i32 s8, 0x4100
	s_cbranch_scc1 .Lxn_top
.Lxn_exit:
	s_waitcnt vmcnt(0)
.LBB0_122:
	s_cmp_lt_i32 s93, 2
	s_cbranch_scc1 .LBB0_172
	v_mov_b32_e32 v0, 0
	v_readlane_b32 s4, v252, 2
	v_mbcnt_lo_u32_b32 v0, -1, v0
	v_readlane_b32 s5, v252, 3
	v_mbcnt_hi_u32_b32 v0, -1, v0
	s_waitcnt vmcnt(0)
	v_sub_u32_e32 v0, 0, v0
	v_cmp_eq_u32_e32 vcc, s90, v0
	s_waitcnt lgkmcnt(0)
	s_barrier
	s_and_saveexec_b64 s[4:5], vcc
	s_cbranch_execz .LBB0_171
	v_readlane_b32 s6, v252, 4
	s_waitcnt vmcnt(0) expcnt(0) lgkmcnt(0)
	s_nop 0
	v_mov_b32_e32 v0, s6
	ds_read_b32 v2, v0
	ds_read_b32 v0, v0 offset:4
	s_waitcnt lgkmcnt(1)
	v_cmp_ne_u32_e32 vcc, 0, v2
	s_cbranch_vccnz .LBB0_139
	v_readlane_b32 s6, v252, 0
	v_readlane_b32 s7, v252, 1
	s_load_dwordx2 s[10:11], s[6:7], 0x4
	s_add_u32 s6, s0, 0x4200
	s_addc_u32 s7, s1, 0
	s_add_u32 s8, s0, 0x4400
	s_addc_u32 s9, s1, 0
	s_waitcnt lgkmcnt(0)
	s_mul_i32 s50, s10, s85
	s_add_u32 s10, s0, 0x4500
	s_mul_i32 s50, s50, s11
	s_addc_u32 s11, s1, 0
	s_add_u32 s12, s0, 0x4600
	s_addc_u32 s13, s1, 0
	s_add_u32 s14, s0, 0x4700
	s_addc_u32 s15, s1, 0
	s_add_u32 s16, s0, 0x4800
	s_addc_u32 s17, s1, 0
	s_add_u32 s18, s0, 0x4900
	s_addc_u32 s19, s1, 0
	s_add_u32 s20, s0, 0x4a00
	s_addc_u32 s21, s1, 0
	s_add_u32 s22, s0, 0x4b00
	s_addc_u32 s23, s1, 0
	s_add_u32 s24, s0, 0x4c00
	s_addc_u32 s25, s1, 0
	s_add_u32 s26, s0, 0x4d00
	s_addc_u32 s27, s1, 0
	s_add_u32 s28, s0, 0x4e00
	s_addc_u32 s29, s1, 0
	s_add_u32 s30, s0, 0x4f00
	s_addc_u32 s31, s1, 0
	s_add_u32 s34, s0, 0x5000
	s_addc_u32 s35, s1, 0
	s_add_u32 s36, s0, 0x5100
	s_addc_u32 s37, s1, 0
	s_add_u32 s38, s0, 0x5200
	s_addc_u32 s39, s1, 0
	s_add_u32 s40, s0, 0x5300
	s_addc_u32 s41, s1, 0
	s_mov_b32 s51, 1
	v_mov_b32_e32 v16, 0
	s_branch .LBB0_127
